# grid barrier early L2 write-back by every 4th arriver of each XCC (8 per XCC) instead of arrivers 0 and 16
# baseline (speedup 1.0000x reference)
; __device__ __forceinline__ void grid_barrier(unsigned* bar, unsigned k, unsigned info, int swave) {
;     ...
;       const unsigned old = __hip_atomic_fetch_add(bar + 64 * (8 + myxcc), 1u, __ATOMIC_RELAXED, __HIP_MEMORY_SCOPE_AGENT);
;       if (old + 1u == k * nmine) {
;         __builtin_amdgcn_fence(__ATOMIC_RELEASE, "agent");
;         asm volatile("s_waitcnt vmcnt(0)" ::: "memory");
;         __hip_atomic_fetch_add(bar + 64 * 16, 1u, __ATOMIC_RELAXED, __HIP_MEMORY_SCOPE_AGENT);
;       }
.LBB0_30:
	s_or_b64 exec, exec, s[2:3]
	s_waitcnt vmcnt(0)
	v_readfirstlane_b32 s2, v1
	v_readlane_b32 s3, v247, 43
	s_nop 0
	v_add3_u32 v0, s2, v0, 1
	v_readlane_b32 s2, v248, 60
	s_mul_i32 s2, s3, s2
	s_nop 0
	v_readlane_b32 s4, v248, 60
	s_sub_i32 s4, s2, s4
	s_add_i32 s4, s4, 1
	v_subrev_u32_e32 v1, s4, v0
	v_and_b32_e32 v1, 3, v1
	v_cmp_eq_u32_e32 vcc, 0, v1
	s_cbranch_vccz .Lxb_noflush
	buffer_wbl2 sc1
